# P1 epilogue: streaming (nt) stores for the z column tiles that are only read two phases later (gate columns), default policy for the tiles P2 reads next
# speedup vs baseline: 1.0153x; 1.0153x over previous
; __device__ __forceinline__ unsigned pk2(float lo, float hi) { f32x2 v = {lo, hi}; bf16x2_t b = __builtin_convertvector(v, bf16x2_t); return __builtin_bit_cast(unsigned, b); }
; __device__ __forceinline__ float ss_total(const float* ss, int row) { const f32x4* sp = (const f32x4*)(ss + (size_t)row * 16); const f32x4 a = sp[0], b = sp[1], c = sp[2], d = sp[3];
;     return (((a[0] + a[1]) + (a[2] + a[3])) + ((b[0] + b[1]) + (b[2] + b[3]))) + (((c[0] + c[1]) + (c[2] + c[3])) + ((d[0] + d[1]) + (d[2] + d[3]))); }
;     __device__ __forceinline__ void operator()(const f32x4 (&acc)[2][2][4][2], const pg8::Unit& u, int wr, int wc, int fr, int fq) const {
;         const int row0 = u.pm * 256 + wr * 64 + fr, col0 = u.pn * 256 + wc * 32 + 8 * fq;
; #pragma unroll
;         for (int ai = 0; ai < 2; ++ai)
; #pragma unroll
;             for (int m = 0; m < 4; ++m) { const int row = row0 + ai * 128 + m * 16; const float rs = rsqrtf(ss_total(ss, row) * (1.f / 1024.f) + EPS);
;                 bf16_t* rowp = O + (size_t)row * ldc + col0;
; #pragma unroll
;                 for (int bj = 0; bj < 2; ++bj) { const f32x4 v0 = acc[ai][bj][m][0] * rs, v1 = acc[ai][bj][m][1] * rs;
;                     u32x4 w; w.x = pk2(v0[0], v0[1]); w.y = pk2(v0[2], v0[3]); w.z = pk2(v1[0], v1[1]); w.w = pk2(v1[2], v1[3]);
;                     *(u32x4*)(rowp + bj * 128) = w; } }
.LBB0_133:
	s_cmp_ge_u32 s82, 16
	s_cbranch_scc1 .Lp1_epi_nt
	v_lshl_add_u32 v156, s83, 8, v159
	v_ashrrev_i32_e32 v157, 31, v156
	v_lshlrev_b64 v[152:153], 6, v[156:157]
	v_lshl_add_u64 v[172:173], s[22:23], 0, v[152:153]
	flat_load_dwordx4 v[152:155], v[172:173]
	flat_load_dwordx4 v[164:167], v[172:173] offset:16
	flat_load_dwordx4 v[168:171], v[172:173] offset:32
	s_nop 0
	flat_load_dwordx4 v[172:175], v[172:173] offset:48
	v_lshl_or_b32 v176, s82, 8, v161
	v_ashrrev_i32_e32 v177, 31, v176
	v_readlane_b32 s84, v250, 44
	s_waitcnt vmcnt(0) lgkmcnt(0)
	v_mov_b32_e32 v178, v152
	v_mov_b32_e32 v179, v168
	v_mov_b32_e32 v168, v153
	v_pk_add_f32 v[152:153], v[178:179], v[168:169]
	v_mov_b32_e32 v168, v154
	v_mov_b32_e32 v169, v170
	v_mov_b32_e32 v170, v155
	v_pk_add_f32 v[154:155], v[168:169], v[170:171]
	s_nop 0
	v_pk_add_f32 v[152:153], v[152:153], v[154:155]
	v_mov_b32_e32 v154, v164
	v_mov_b32_e32 v155, v172
	v_mov_b32_e32 v172, v165
	v_mov_b32_e32 v164, v166
	v_mov_b32_e32 v165, v174
	v_mov_b32_e32 v174, v167
	v_pk_add_f32 v[154:155], v[154:155], v[172:173]
	v_pk_add_f32 v[164:165], v[164:165], v[174:175]
	s_nop 0
	v_pk_add_f32 v[154:155], v[154:155], v[164:165]
	s_nop 0
	v_pk_add_f32 v[152:153], v[152:153], v[154:155]
	v_lshlrev_b64 v[154:155], 1, v[176:177]
	v_add_f32_e32 v152, v152, v153
	v_fmamk_f32 v152, v152, 0x3a800000, v190
	v_cmp_gt_f32_e32 vcc, s66, v152
	v_mul_f32_e32 v153, 0x4b800000, v152
	s_nop 0
	v_cndmask_b32_e32 v152, v152, v153, vcc
	v_rsq_f32_e32 v152, v152
	s_nop 0
	v_mul_f32_e32 v153, 0x45800000, v152
	v_cndmask_b32_e32 v164, v152, v153, vcc
	v_mov_b64_e32 v[152:153], s[14:15]
	v_mad_i64_i32 v[166:167], s[4:5], v156, s67, v[152:153]
	v_pk_mul_f32 v[128:129], v[128:129], v[164:165] op_sel_hi:[1,0]
	v_pk_mul_f32 v[126:127], v[126:127], v[164:165] op_sel_hi:[1,0]
	v_pk_mul_f32 v[168:169], v[124:125], v[164:165] op_sel_hi:[1,0]
	v_pk_mul_f32 v[124:125], v[122:123], v[164:165] op_sel_hi:[1,0]
	v_lshl_add_u64 v[166:167], v[166:167], 0, v[154:155]
	v_cvt_pk_bf16_f32 v122, v126, v127
	v_cvt_pk_bf16_f32 v123, v128, v129
	v_cvt_pk_bf16_f32 v124, v124, v125
	v_cvt_pk_bf16_f32 v125, v168, v169
	flat_store_dwordx4 v[166:167], v[122:125]
	v_pk_mul_f32 v[120:121], v[120:121], v[164:165] op_sel_hi:[1,0]
	v_pk_mul_f32 v[118:119], v[118:119], v[164:165] op_sel_hi:[1,0]
	v_pk_mul_f32 v[122:123], v[116:117], v[164:165] op_sel_hi:[1,0]
	v_pk_mul_f32 v[116:117], v[114:115], v[164:165] op_sel_hi:[1,0]
	v_or_b32_e32 v164, 16, v156
	v_cvt_pk_bf16_f32 v114, v118, v119
	v_cvt_pk_bf16_f32 v115, v120, v121
	v_cvt_pk_bf16_f32 v116, v116, v117
	v_cvt_pk_bf16_f32 v117, v122, v123
	v_ashrrev_i32_e32 v165, 31, v164
	flat_store_dwordx4 v[166:167], v[114:117] offset:256
	s_nop 1
	v_lshlrev_b64 v[114:115], 6, v[164:165]
	v_lshl_add_u64 v[126:127], s[22:23], 0, v[114:115]
	flat_load_dwordx4 v[114:117], v[126:127]
	flat_load_dwordx4 v[118:121], v[126:127] offset:16
	flat_load_dwordx4 v[122:125], v[126:127] offset:32
	s_nop 0
	flat_load_dwordx4 v[126:129], v[126:127] offset:48
	s_waitcnt vmcnt(0) lgkmcnt(0)
	v_mov_b32_e32 v166, v114
	v_mov_b32_e32 v167, v122
	v_mov_b32_e32 v122, v115
	v_pk_add_f32 v[114:115], v[166:167], v[122:123]
	v_mov_b32_e32 v122, v116
	v_mov_b32_e32 v123, v124
	v_mov_b32_e32 v124, v117
	v_pk_add_f32 v[116:117], v[122:123], v[124:125]
	s_nop 0
	v_pk_add_f32 v[114:115], v[114:115], v[116:117]
	v_mov_b32_e32 v116, v118
	v_mov_b32_e32 v117, v126
	v_mov_b32_e32 v126, v119
	v_mov_b32_e32 v118, v120
	v_mov_b32_e32 v119, v128
	v_mov_b32_e32 v128, v121
	v_pk_add_f32 v[116:117], v[116:117], v[126:127]
	v_pk_add_f32 v[118:119], v[118:119], v[128:129]
	s_nop 0
	v_pk_add_f32 v[116:117], v[116:117], v[118:119]
	s_nop 0
	v_pk_add_f32 v[114:115], v[114:115], v[116:117]
	v_mad_i64_i32 v[116:117], s[4:5], v164, s67, v[152:153]
	v_add_f32_e32 v114, v114, v115
	v_fmamk_f32 v114, v114, 0x3a800000, v190
	v_cmp_gt_f32_e32 vcc, s66, v114
	v_mul_f32_e32 v115, 0x4b800000, v114
	v_lshl_add_u64 v[116:117], v[116:117], 0, v[154:155]
	v_cndmask_b32_e32 v114, v114, v115, vcc
	v_rsq_f32_e32 v114, v114
	s_nop 0
	v_mul_f32_e32 v115, 0x45800000, v114
	v_cndmask_b32_e32 v114, v114, v115, vcc
	v_pk_mul_f32 v[112:113], v[112:113], v[114:115] op_sel_hi:[1,0]
	v_pk_mul_f32 v[110:111], v[110:111], v[114:115] op_sel_hi:[1,0]
	v_pk_mul_f32 v[118:119], v[108:109], v[114:115] op_sel_hi:[1,0]
	v_pk_mul_f32 v[108:109], v[106:107], v[114:115] op_sel_hi:[1,0]
	v_cvt_pk_bf16_f32 v106, v110, v111
	v_cvt_pk_bf16_f32 v107, v112, v113
	v_cvt_pk_bf16_f32 v108, v108, v109
	v_cvt_pk_bf16_f32 v109, v118, v119
	flat_store_dwordx4 v[116:117], v[106:109]
	v_pk_mul_f32 v[104:105], v[104:105], v[114:115] op_sel_hi:[1,0]
	v_pk_mul_f32 v[102:103], v[102:103], v[114:115] op_sel_hi:[1,0]
	v_pk_mul_f32 v[106:107], v[100:101], v[114:115] op_sel_hi:[1,0]
	v_pk_mul_f32 v[100:101], v[98:99], v[114:115] op_sel_hi:[1,0]
	v_or_b32_e32 v114, 32, v156
	v_cvt_pk_bf16_f32 v98, v102, v103
	v_cvt_pk_bf16_f32 v99, v104, v105
	v_cvt_pk_bf16_f32 v100, v100, v101
	v_cvt_pk_bf16_f32 v101, v106, v107
	v_ashrrev_i32_e32 v115, 31, v114
	flat_store_dwordx4 v[116:117], v[98:101] offset:256
	s_nop 1
	v_lshlrev_b64 v[98:99], 6, v[114:115]
	v_lshl_add_u64 v[110:111], s[22:23], 0, v[98:99]
	flat_load_dwordx4 v[98:101], v[110:111]
	flat_load_dwordx4 v[102:105], v[110:111] offset:16
	flat_load_dwordx4 v[106:109], v[110:111] offset:32
	s_nop 0
	flat_load_dwordx4 v[110:113], v[110:111] offset:48
	s_waitcnt vmcnt(0) lgkmcnt(0)
; __device__ __forceinline__ unsigned pk2(float lo, float hi) { f32x2 v = {lo, hi}; bf16x2_t b = __builtin_convertvector(v, bf16x2_t); return __builtin_bit_cast(unsigned, b); }
; __device__ __forceinline__ float ss_total(const float* ss, int row) { const f32x4* sp = (const f32x4*)(ss + (size_t)row * 16); const f32x4 a = sp[0], b = sp[1], c = sp[2], d = sp[3];
;     return (((a[0] + a[1]) + (a[2] + a[3])) + ((b[0] + b[1]) + (b[2] + b[3]))) + (((c[0] + c[1]) + (c[2] + c[3])) + ((d[0] + d[1]) + (d[2] + d[3]))); }
;     __device__ __forceinline__ void operator()(const f32x4 (&acc)[2][2][4][2], const pg8::Unit& u, int wr, int wc, int fr, int fq) const {
;         const int row0 = u.pm * 256 + wr * 64 + fr, col0 = u.pn * 256 + wc * 32 + 8 * fq;
; #pragma unroll
;         for (int ai = 0; ai < 2; ++ai)
; #pragma unroll
;             for (int m = 0; m < 4; ++m) { const int row = row0 + ai * 128 + m * 16; const float rs = rsqrtf(ss_total(ss, row) * (1.f / 1024.f) + EPS);
;                 bf16_t* rowp = O + (size_t)row * ldc + col0;
; #pragma unroll
;                 for (int bj = 0; bj < 2; ++bj) { const f32x4 v0 = acc[ai][bj][m][0] * rs, v1 = acc[ai][bj][m][1] * rs;
;                     u32x4 w; w.x = pk2(v0[0], v0[1]); w.y = pk2(v0[2], v0[3]); w.z = pk2(v1[0], v1[1]); w.w = pk2(v1[2], v1[3]);
;                     *(u32x4*)(rowp + bj * 128) = w; } }
	v_mov_b32_e32 v116, v98
	v_mov_b32_e32 v117, v106
	v_mov_b32_e32 v106, v99
	v_pk_add_f32 v[98:99], v[116:117], v[106:107]
	v_mov_b32_e32 v106, v100
	v_mov_b32_e32 v107, v108
	v_mov_b32_e32 v108, v101
	v_pk_add_f32 v[100:101], v[106:107], v[108:109]
	s_nop 0
	v_pk_add_f32 v[98:99], v[98:99], v[100:101]
	v_mov_b32_e32 v100, v102
	v_mov_b32_e32 v101, v110
	v_mov_b32_e32 v110, v103
	v_mov_b32_e32 v102, v104
	v_mov_b32_e32 v103, v112
	v_mov_b32_e32 v112, v105
	v_pk_add_f32 v[100:101], v[100:101], v[110:111]
	v_pk_add_f32 v[102:103], v[102:103], v[112:113]
	s_nop 0
	v_pk_add_f32 v[100:101], v[100:101], v[102:103]
	s_nop 0
	v_pk_add_f32 v[98:99], v[98:99], v[100:101]
	v_mad_i64_i32 v[100:101], s[4:5], v114, s67, v[152:153]
	v_add_f32_e32 v98, v98, v99
	v_fmamk_f32 v98, v98, 0x3a800000, v190
	v_cmp_gt_f32_e32 vcc, s66, v98
	v_mul_f32_e32 v99, 0x4b800000, v98
	v_lshl_add_u64 v[100:101], v[100:101], 0, v[154:155]
	v_cndmask_b32_e32 v98, v98, v99, vcc
	v_rsq_f32_e32 v98, v98
	s_nop 0
	v_mul_f32_e32 v99, 0x45800000, v98
	v_cndmask_b32_e32 v98, v98, v99, vcc
	v_pk_mul_f32 v[96:97], v[96:97], v[98:99] op_sel_hi:[1,0]
	v_pk_mul_f32 v[94:95], v[94:95], v[98:99] op_sel_hi:[1,0]
	v_pk_mul_f32 v[102:103], v[92:93], v[98:99] op_sel_hi:[1,0]
	v_pk_mul_f32 v[92:93], v[90:91], v[98:99] op_sel_hi:[1,0]
	v_cvt_pk_bf16_f32 v90, v94, v95
	v_cvt_pk_bf16_f32 v91, v96, v97
	v_cvt_pk_bf16_f32 v92, v92, v93
	v_cvt_pk_bf16_f32 v93, v102, v103
	flat_store_dwordx4 v[100:101], v[90:93]
	v_pk_mul_f32 v[88:89], v[88:89], v[98:99] op_sel_hi:[1,0]
	v_pk_mul_f32 v[86:87], v[86:87], v[98:99] op_sel_hi:[1,0]
	v_pk_mul_f32 v[90:91], v[84:85], v[98:99] op_sel_hi:[1,0]
	v_pk_mul_f32 v[84:85], v[82:83], v[98:99] op_sel_hi:[1,0]
	v_or_b32_e32 v98, 48, v156
	v_cvt_pk_bf16_f32 v82, v86, v87
	v_cvt_pk_bf16_f32 v83, v88, v89
	v_cvt_pk_bf16_f32 v84, v84, v85
	v_cvt_pk_bf16_f32 v85, v90, v91
	v_ashrrev_i32_e32 v99, 31, v98
	flat_store_dwordx4 v[100:101], v[82:85] offset:256
	s_nop 1
	v_lshlrev_b64 v[82:83], 6, v[98:99]
	v_lshl_add_u64 v[94:95], s[22:23], 0, v[82:83]
	flat_load_dwordx4 v[82:85], v[94:95]
	flat_load_dwordx4 v[86:89], v[94:95] offset:16
	flat_load_dwordx4 v[90:93], v[94:95] offset:32
	s_nop 0
	flat_load_dwordx4 v[94:97], v[94:95] offset:48
	s_waitcnt vmcnt(0) lgkmcnt(0)
	v_mov_b32_e32 v100, v82
	v_mov_b32_e32 v101, v90
	v_mov_b32_e32 v90, v83
	v_pk_add_f32 v[82:83], v[100:101], v[90:91]
	v_mov_b32_e32 v90, v84
	v_mov_b32_e32 v91, v92
	v_mov_b32_e32 v92, v85
	v_pk_add_f32 v[84:85], v[90:91], v[92:93]
	s_nop 0
	v_pk_add_f32 v[82:83], v[82:83], v[84:85]
	v_mov_b32_e32 v84, v86
	v_mov_b32_e32 v85, v94
	v_mov_b32_e32 v94, v87
	v_mov_b32_e32 v86, v88
	v_mov_b32_e32 v87, v96
	v_mov_b32_e32 v96, v89
	v_pk_add_f32 v[84:85], v[84:85], v[94:95]
	v_pk_add_f32 v[86:87], v[86:87], v[96:97]
	s_nop 0
	v_pk_add_f32 v[84:85], v[84:85], v[86:87]
	s_nop 0
	v_pk_add_f32 v[82:83], v[82:83], v[84:85]
	v_mad_i64_i32 v[84:85], s[4:5], v98, s67, v[152:153]
	v_add_f32_e32 v82, v82, v83
	v_fmamk_f32 v82, v82, 0x3a800000, v190
	v_cmp_gt_f32_e32 vcc, s66, v82
	v_mul_f32_e32 v83, 0x4b800000, v82
	v_lshl_add_u64 v[84:85], v[84:85], 0, v[154:155]
	v_cndmask_b32_e32 v82, v82, v83, vcc
	v_rsq_f32_e32 v82, v82
	s_nop 0
	v_mul_f32_e32 v83, 0x45800000, v82
	v_cndmask_b32_e32 v82, v82, v83, vcc
	v_pk_mul_f32 v[80:81], v[80:81], v[82:83] op_sel_hi:[1,0]
	v_pk_mul_f32 v[78:79], v[78:79], v[82:83] op_sel_hi:[1,0]
	v_pk_mul_f32 v[86:87], v[76:77], v[82:83] op_sel_hi:[1,0]
	v_pk_mul_f32 v[76:77], v[74:75], v[82:83] op_sel_hi:[1,0]
	v_cvt_pk_bf16_f32 v74, v78, v79
	v_cvt_pk_bf16_f32 v75, v80, v81
	v_cvt_pk_bf16_f32 v76, v76, v77
	v_cvt_pk_bf16_f32 v77, v86, v87
	flat_store_dwordx4 v[84:85], v[74:77]
	v_pk_mul_f32 v[72:73], v[72:73], v[82:83] op_sel_hi:[1,0]
	v_pk_mul_f32 v[70:71], v[70:71], v[82:83] op_sel_hi:[1,0]
	v_pk_mul_f32 v[74:75], v[68:69], v[82:83] op_sel_hi:[1,0]
	v_pk_mul_f32 v[68:69], v[66:67], v[82:83] op_sel_hi:[1,0]
	v_add_u32_e32 v82, 0x80, v156
	v_cvt_pk_bf16_f32 v66, v70, v71
	v_cvt_pk_bf16_f32 v67, v72, v73
	v_cvt_pk_bf16_f32 v68, v68, v69
	v_cvt_pk_bf16_f32 v69, v74, v75
	v_ashrrev_i32_e32 v83, 31, v82
	flat_store_dwordx4 v[84:85], v[66:69] offset:256
	s_nop 1
	v_lshlrev_b64 v[66:67], 6, v[82:83]
	v_lshl_add_u64 v[78:79], s[22:23], 0, v[66:67]
	flat_load_dwordx4 v[66:69], v[78:79]
	flat_load_dwordx4 v[70:73], v[78:79] offset:16
	flat_load_dwordx4 v[74:77], v[78:79] offset:32
	s_nop 0
	flat_load_dwordx4 v[78:81], v[78:79] offset:48
	s_waitcnt vmcnt(0) lgkmcnt(0)
	v_mov_b32_e32 v84, v66
	v_mov_b32_e32 v85, v74
	v_mov_b32_e32 v74, v67
	v_pk_add_f32 v[66:67], v[84:85], v[74:75]
	v_mov_b32_e32 v74, v68
	v_mov_b32_e32 v75, v76
	v_mov_b32_e32 v76, v69
	v_pk_add_f32 v[68:69], v[74:75], v[76:77]
	s_nop 0
	v_pk_add_f32 v[66:67], v[66:67], v[68:69]
	v_mov_b32_e32 v68, v70
	v_mov_b32_e32 v69, v78
	v_mov_b32_e32 v78, v71
	v_mov_b32_e32 v70, v72
	v_mov_b32_e32 v71, v80
	v_mov_b32_e32 v80, v73
	v_pk_add_f32 v[68:69], v[68:69], v[78:79]
	v_pk_add_f32 v[70:71], v[70:71], v[80:81]
	s_nop 0
	v_pk_add_f32 v[68:69], v[68:69], v[70:71]
	s_nop 0
	v_pk_add_f32 v[66:67], v[66:67], v[68:69]
	v_mad_i64_i32 v[68:69], s[4:5], v82, s67, v[152:153]
	v_add_f32_e32 v66, v66, v67
	v_fmamk_f32 v66, v66, 0x3a800000, v190
	v_cmp_gt_f32_e32 vcc, s66, v66
	v_mul_f32_e32 v67, 0x4b800000, v66
	v_lshl_add_u64 v[68:69], v[68:69], 0, v[154:155]
	v_cndmask_b32_e32 v66, v66, v67, vcc
	v_rsq_f32_e32 v66, v66
	s_nop 0
	v_mul_f32_e32 v67, 0x45800000, v66
	v_cndmask_b32_e32 v66, v66, v67, vcc
	v_pk_mul_f32 v[64:65], v[64:65], v[66:67] op_sel_hi:[1,0]
	v_pk_mul_f32 v[62:63], v[62:63], v[66:67] op_sel_hi:[1,0]
	v_pk_mul_f32 v[70:71], v[60:61], v[66:67] op_sel_hi:[1,0]
	v_pk_mul_f32 v[60:61], v[58:59], v[66:67] op_sel_hi:[1,0]
	v_cvt_pk_bf16_f32 v58, v62, v63
	v_cvt_pk_bf16_f32 v59, v64, v65
	v_cvt_pk_bf16_f32 v60, v60, v61
	v_cvt_pk_bf16_f32 v61, v70, v71
	flat_store_dwordx4 v[68:69], v[58:61]
	v_pk_mul_f32 v[56:57], v[56:57], v[66:67] op_sel_hi:[1,0]
	v_pk_mul_f32 v[54:55], v[54:55], v[66:67] op_sel_hi:[1,0]
	v_pk_mul_f32 v[58:59], v[52:53], v[66:67] op_sel_hi:[1,0]
	v_pk_mul_f32 v[52:53], v[50:51], v[66:67] op_sel_hi:[1,0]
	v_add_u32_e32 v66, 0x90, v156
	v_cvt_pk_bf16_f32 v50, v54, v55
	v_cvt_pk_bf16_f32 v51, v56, v57
	v_cvt_pk_bf16_f32 v52, v52, v53
	v_cvt_pk_bf16_f32 v53, v58, v59
	v_ashrrev_i32_e32 v67, 31, v66
	flat_store_dwordx4 v[68:69], v[50:53] offset:256
	s_nop 1
	v_lshlrev_b64 v[50:51], 6, v[66:67]
	v_lshl_add_u64 v[62:63], s[22:23], 0, v[50:51]
	flat_load_dwordx4 v[50:53], v[62:63]
	flat_load_dwordx4 v[54:57], v[62:63] offset:16
	flat_load_dwordx4 v[58:61], v[62:63] offset:32
	s_nop 0
	flat_load_dwordx4 v[62:65], v[62:63] offset:48
	s_waitcnt vmcnt(0) lgkmcnt(0)
; __device__ __forceinline__ unsigned pk2(float lo, float hi) { f32x2 v = {lo, hi}; bf16x2_t b = __builtin_convertvector(v, bf16x2_t); return __builtin_bit_cast(unsigned, b); }
; __device__ __forceinline__ float ss_total(const float* ss, int row) { const f32x4* sp = (const f32x4*)(ss + (size_t)row * 16); const f32x4 a = sp[0], b = sp[1], c = sp[2], d = sp[3];
;     return (((a[0] + a[1]) + (a[2] + a[3])) + ((b[0] + b[1]) + (b[2] + b[3]))) + (((c[0] + c[1]) + (c[2] + c[3])) + ((d[0] + d[1]) + (d[2] + d[3]))); }
;     __device__ __forceinline__ void operator()(const f32x4 (&acc)[2][2][4][2], const pg8::Unit& u, int wr, int wc, int fr, int fq) const {
;         const int row0 = u.pm * 256 + wr * 64 + fr, col0 = u.pn * 256 + wc * 32 + 8 * fq;
; #pragma unroll
;         for (int ai = 0; ai < 2; ++ai)
; #pragma unroll
;             for (int m = 0; m < 4; ++m) { const int row = row0 + ai * 128 + m * 16; const float rs = rsqrtf(ss_total(ss, row) * (1.f / 1024.f) + EPS);
;                 bf16_t* rowp = O + (size_t)row * ldc + col0;
; #pragma unroll
;                 for (int bj = 0; bj < 2; ++bj) { const f32x4 v0 = acc[ai][bj][m][0] * rs, v1 = acc[ai][bj][m][1] * rs;
;                     u32x4 w; w.x = pk2(v0[0], v0[1]); w.y = pk2(v0[2], v0[3]); w.z = pk2(v1[0], v1[1]); w.w = pk2(v1[2], v1[3]);
;                     *(u32x4*)(rowp + bj * 128) = w; } }
	v_mov_b32_e32 v68, v50
	v_mov_b32_e32 v69, v58
	v_mov_b32_e32 v58, v51
	v_pk_add_f32 v[50:51], v[68:69], v[58:59]
	v_mov_b32_e32 v58, v52
	v_mov_b32_e32 v59, v60
	v_mov_b32_e32 v60, v53
	v_pk_add_f32 v[52:53], v[58:59], v[60:61]
	s_nop 0
	v_pk_add_f32 v[50:51], v[50:51], v[52:53]
	v_mov_b32_e32 v52, v54
	v_mov_b32_e32 v53, v62
	v_mov_b32_e32 v62, v55
	v_mov_b32_e32 v54, v56
	v_mov_b32_e32 v55, v64
	v_mov_b32_e32 v64, v57
	v_pk_add_f32 v[52:53], v[52:53], v[62:63]
	v_pk_add_f32 v[54:55], v[54:55], v[64:65]
	s_nop 0
	v_pk_add_f32 v[52:53], v[52:53], v[54:55]
	s_nop 0
	v_pk_add_f32 v[50:51], v[50:51], v[52:53]
	v_mad_i64_i32 v[52:53], s[4:5], v66, s67, v[152:153]
	v_add_f32_e32 v50, v50, v51
	v_fmamk_f32 v50, v50, 0x3a800000, v190
	v_cmp_gt_f32_e32 vcc, s66, v50
	v_mul_f32_e32 v51, 0x4b800000, v50
	v_lshl_add_u64 v[52:53], v[52:53], 0, v[154:155]
	v_cndmask_b32_e32 v50, v50, v51, vcc
	v_rsq_f32_e32 v50, v50
	s_nop 0
	v_mul_f32_e32 v51, 0x45800000, v50
	v_cndmask_b32_e32 v50, v50, v51, vcc
	v_pk_mul_f32 v[48:49], v[48:49], v[50:51] op_sel_hi:[1,0]
	v_pk_mul_f32 v[46:47], v[46:47], v[50:51] op_sel_hi:[1,0]
	v_pk_mul_f32 v[54:55], v[44:45], v[50:51] op_sel_hi:[1,0]
	v_pk_mul_f32 v[44:45], v[42:43], v[50:51] op_sel_hi:[1,0]
	v_cvt_pk_bf16_f32 v42, v46, v47
	v_cvt_pk_bf16_f32 v43, v48, v49
	v_cvt_pk_bf16_f32 v44, v44, v45
	v_cvt_pk_bf16_f32 v45, v54, v55
	flat_store_dwordx4 v[52:53], v[42:45]
	v_pk_mul_f32 v[40:41], v[40:41], v[50:51] op_sel_hi:[1,0]
	v_pk_mul_f32 v[38:39], v[38:39], v[50:51] op_sel_hi:[1,0]
	v_pk_mul_f32 v[42:43], v[36:37], v[50:51] op_sel_hi:[1,0]
	v_pk_mul_f32 v[36:37], v[34:35], v[50:51] op_sel_hi:[1,0]
	v_add_u32_e32 v50, 0xa0, v156
	v_cvt_pk_bf16_f32 v34, v38, v39
	v_cvt_pk_bf16_f32 v35, v40, v41
	v_cvt_pk_bf16_f32 v36, v36, v37
	v_cvt_pk_bf16_f32 v37, v42, v43
	v_ashrrev_i32_e32 v51, 31, v50
	flat_store_dwordx4 v[52:53], v[34:37] offset:256
	s_nop 1
	v_lshlrev_b64 v[34:35], 6, v[50:51]
	v_lshl_add_u64 v[46:47], s[22:23], 0, v[34:35]
	flat_load_dwordx4 v[34:37], v[46:47]
	flat_load_dwordx4 v[38:41], v[46:47] offset:16
	flat_load_dwordx4 v[42:45], v[46:47] offset:32
	s_nop 0
	flat_load_dwordx4 v[46:49], v[46:47] offset:48
	s_waitcnt vmcnt(0) lgkmcnt(0)
	v_mov_b32_e32 v52, v34
	v_mov_b32_e32 v53, v42
	v_mov_b32_e32 v42, v35
	v_pk_add_f32 v[34:35], v[52:53], v[42:43]
	v_mov_b32_e32 v42, v36
	v_mov_b32_e32 v43, v44
	v_mov_b32_e32 v44, v37
	v_pk_add_f32 v[36:37], v[42:43], v[44:45]
	s_nop 0
	v_pk_add_f32 v[34:35], v[34:35], v[36:37]
	v_mov_b32_e32 v36, v38
	v_mov_b32_e32 v37, v46
	v_mov_b32_e32 v46, v39
	v_mov_b32_e32 v38, v40
	v_mov_b32_e32 v39, v48
	v_mov_b32_e32 v48, v41
	v_pk_add_f32 v[36:37], v[36:37], v[46:47]
	v_pk_add_f32 v[38:39], v[38:39], v[48:49]
	s_nop 0
	v_pk_add_f32 v[36:37], v[36:37], v[38:39]
	s_nop 0
	v_pk_add_f32 v[34:35], v[34:35], v[36:37]
	v_mad_i64_i32 v[36:37], s[4:5], v50, s67, v[152:153]
	v_add_f32_e32 v34, v34, v35
	v_fmamk_f32 v34, v34, 0x3a800000, v190
	v_cmp_gt_f32_e32 vcc, s66, v34
	v_mul_f32_e32 v35, 0x4b800000, v34
	v_lshl_add_u64 v[36:37], v[36:37], 0, v[154:155]
	v_cndmask_b32_e32 v34, v34, v35, vcc
	v_rsq_f32_e32 v34, v34
	s_nop 0
	v_mul_f32_e32 v35, 0x45800000, v34
	v_cndmask_b32_e32 v34, v34, v35, vcc
	v_pk_mul_f32 v[32:33], v[32:33], v[34:35] op_sel_hi:[1,0]
	v_pk_mul_f32 v[30:31], v[30:31], v[34:35] op_sel_hi:[1,0]
	v_pk_mul_f32 v[38:39], v[28:29], v[34:35] op_sel_hi:[1,0]
	v_pk_mul_f32 v[28:29], v[26:27], v[34:35] op_sel_hi:[1,0]
	v_cvt_pk_bf16_f32 v26, v30, v31
	v_cvt_pk_bf16_f32 v27, v32, v33
	v_cvt_pk_bf16_f32 v28, v28, v29
	v_cvt_pk_bf16_f32 v29, v38, v39
	flat_store_dwordx4 v[36:37], v[26:29]
	v_pk_mul_f32 v[24:25], v[24:25], v[34:35] op_sel_hi:[1,0]
	v_pk_mul_f32 v[22:23], v[22:23], v[34:35] op_sel_hi:[1,0]
	v_pk_mul_f32 v[26:27], v[20:21], v[34:35] op_sel_hi:[1,0]
	v_pk_mul_f32 v[20:21], v[18:19], v[34:35] op_sel_hi:[1,0]
	v_add_u32_e32 v34, 0xb0, v156
	v_cvt_pk_bf16_f32 v18, v22, v23
	v_cvt_pk_bf16_f32 v19, v24, v25
	v_cvt_pk_bf16_f32 v20, v20, v21
	v_cvt_pk_bf16_f32 v21, v26, v27
	v_ashrrev_i32_e32 v35, 31, v34
	flat_store_dwordx4 v[36:37], v[18:21] offset:256
	s_nop 1
	v_lshlrev_b64 v[18:19], 6, v[34:35]
	v_lshl_add_u64 v[30:31], s[22:23], 0, v[18:19]
	flat_load_dwordx4 v[18:21], v[30:31]
	flat_load_dwordx4 v[22:25], v[30:31] offset:16
	flat_load_dwordx4 v[26:29], v[30:31] offset:32
	s_nop 0
	flat_load_dwordx4 v[30:33], v[30:31] offset:48
	s_waitcnt vmcnt(0) lgkmcnt(0)
	v_mov_b32_e32 v36, v18
	v_mov_b32_e32 v37, v26
	v_mov_b32_e32 v26, v19
	v_pk_add_f32 v[18:19], v[36:37], v[26:27]
	v_mov_b32_e32 v26, v20
	v_mov_b32_e32 v27, v28
	v_mov_b32_e32 v28, v21
	v_pk_add_f32 v[20:21], v[26:27], v[28:29]
	s_nop 0
	v_pk_add_f32 v[18:19], v[18:19], v[20:21]
	v_mov_b32_e32 v20, v22
	v_mov_b32_e32 v21, v30
	v_mov_b32_e32 v30, v23
	v_mov_b32_e32 v22, v24
	v_mov_b32_e32 v23, v32
	v_mov_b32_e32 v32, v25
	v_pk_add_f32 v[20:21], v[20:21], v[30:31]
	v_pk_add_f32 v[22:23], v[22:23], v[32:33]
	s_nop 0
	v_pk_add_f32 v[20:21], v[20:21], v[22:23]
	s_nop 0
	v_pk_add_f32 v[18:19], v[18:19], v[20:21]
	v_mad_i64_i32 v[20:21], s[4:5], v34, s67, v[152:153]
	v_add_f32_e32 v18, v18, v19
	v_fmamk_f32 v18, v18, 0x3a800000, v190
	v_cmp_gt_f32_e32 vcc, s66, v18
	v_mul_f32_e32 v19, 0x4b800000, v18
	v_lshl_add_u64 v[20:21], v[20:21], 0, v[154:155]
	v_cndmask_b32_e32 v18, v18, v19, vcc
	v_rsq_f32_e32 v18, v18
	s_mov_b64 s[4:5], -1
	v_mul_f32_e32 v19, 0x45800000, v18
	v_cndmask_b32_e32 v18, v18, v19, vcc
	v_pk_mul_f32 v[16:17], v[16:17], v[18:19] op_sel_hi:[1,0]
	v_pk_mul_f32 v[14:15], v[14:15], v[18:19] op_sel_hi:[1,0]
	v_pk_mul_f32 v[22:23], v[12:13], v[18:19] op_sel_hi:[1,0]
	v_pk_mul_f32 v[12:13], v[10:11], v[18:19] op_sel_hi:[1,0]
	v_cvt_pk_bf16_f32 v10, v14, v15
	v_cvt_pk_bf16_f32 v11, v16, v17
	v_cvt_pk_bf16_f32 v12, v12, v13
	v_cvt_pk_bf16_f32 v13, v22, v23
	flat_store_dwordx4 v[20:21], v[10:13]
	v_pk_mul_f32 v[8:9], v[8:9], v[18:19] op_sel_hi:[1,0]
	v_pk_mul_f32 v[6:7], v[6:7], v[18:19] op_sel_hi:[1,0]
	v_pk_mul_f32 v[10:11], v[4:5], v[18:19] op_sel_hi:[1,0]
	v_pk_mul_f32 v[4:5], v[2:3], v[18:19] op_sel_hi:[1,0]
	v_cvt_pk_bf16_f32 v2, v6, v7
	v_cvt_pk_bf16_f32 v3, v8, v9
	v_cvt_pk_bf16_f32 v4, v4, v5
	v_cvt_pk_bf16_f32 v5, v10, v11
	s_andn2_b64 vcc, exec, s[38:39]
	flat_store_dwordx4 v[20:21], v[2:5] offset:256
; __device__ __forceinline__ unsigned pk2(float lo, float hi) { f32x2 v = {lo, hi}; bf16x2_t b = __builtin_convertvector(v, bf16x2_t); return __builtin_bit_cast(unsigned, b); }
; __device__ __forceinline__ float ss_total(const float* ss, int row) { const f32x4* sp = (const f32x4*)(ss + (size_t)row * 16); const f32x4 a = sp[0], b = sp[1], c = sp[2], d = sp[3];
;     return (((a[0] + a[1]) + (a[2] + a[3])) + ((b[0] + b[1]) + (b[2] + b[3]))) + (((c[0] + c[1]) + (c[2] + c[3])) + ((d[0] + d[1]) + (d[2] + d[3]))); }
;     __device__ __forceinline__ void operator()(const f32x4 (&acc)[2][2][4][2], const pg8::Unit& u, int wr, int wc, int fr, int fq) const {
;         const int row0 = u.pm * 256 + wr * 64 + fr, col0 = u.pn * 256 + wc * 32 + 8 * fq;
; #pragma unroll
;         for (int ai = 0; ai < 2; ++ai)
; #pragma unroll
;             for (int m = 0; m < 4; ++m) { const int row = row0 + ai * 128 + m * 16; const float rs = rsqrtf(ss_total(ss, row) * (1.f / 1024.f) + EPS);
;                 bf16_t* rowp = O + (size_t)row * ldc + col0;
; #pragma unroll
;                 for (int bj = 0; bj < 2; ++bj) { const f32x4 v0 = acc[ai][bj][m][0] * rs, v1 = acc[ai][bj][m][1] * rs;
;                     u32x4 w; w.x = pk2(v0[0], v0[1]); w.y = pk2(v0[2], v0[3]); w.z = pk2(v1[0], v1[1]); w.w = pk2(v1[2], v1[3]);
;                     *(u32x4*)(rowp + bj * 128) = w; } }
.Lp1_epi_join:
	s_cbranch_vccnz .LBB0_126
	s_branch .Lp1_epi_after
.Lp1_epi_nt:
	v_lshl_add_u32 v156, s83, 8, v159
	v_ashrrev_i32_e32 v157, 31, v156
	v_lshlrev_b64 v[152:153], 6, v[156:157]
	v_lshl_add_u64 v[172:173], s[22:23], 0, v[152:153]
	flat_load_dwordx4 v[152:155], v[172:173]
	flat_load_dwordx4 v[164:167], v[172:173] offset:16
	flat_load_dwordx4 v[168:171], v[172:173] offset:32
	s_nop 0
	flat_load_dwordx4 v[172:175], v[172:173] offset:48
	v_lshl_or_b32 v176, s82, 8, v161
	v_ashrrev_i32_e32 v177, 31, v176
	v_readlane_b32 s84, v250, 44
	s_waitcnt vmcnt(0) lgkmcnt(0)
	v_mov_b32_e32 v178, v152
	v_mov_b32_e32 v179, v168
	v_mov_b32_e32 v168, v153
	v_pk_add_f32 v[152:153], v[178:179], v[168:169]
	v_mov_b32_e32 v168, v154
	v_mov_b32_e32 v169, v170
	v_mov_b32_e32 v170, v155
	v_pk_add_f32 v[154:155], v[168:169], v[170:171]
	s_nop 0
	v_pk_add_f32 v[152:153], v[152:153], v[154:155]
	v_mov_b32_e32 v154, v164
	v_mov_b32_e32 v155, v172
	v_mov_b32_e32 v172, v165
	v_mov_b32_e32 v164, v166
	v_mov_b32_e32 v165, v174
	v_mov_b32_e32 v174, v167
	v_pk_add_f32 v[154:155], v[154:155], v[172:173]
	v_pk_add_f32 v[164:165], v[164:165], v[174:175]
	s_nop 0
	v_pk_add_f32 v[154:155], v[154:155], v[164:165]
	s_nop 0
	v_pk_add_f32 v[152:153], v[152:153], v[154:155]
	v_lshlrev_b64 v[154:155], 1, v[176:177]
	v_add_f32_e32 v152, v152, v153
	v_fmamk_f32 v152, v152, 0x3a800000, v190
	v_cmp_gt_f32_e32 vcc, s66, v152
	v_mul_f32_e32 v153, 0x4b800000, v152
	s_nop 0
	v_cndmask_b32_e32 v152, v152, v153, vcc
	v_rsq_f32_e32 v152, v152
	s_nop 0
	v_mul_f32_e32 v153, 0x45800000, v152
	v_cndmask_b32_e32 v164, v152, v153, vcc
	v_mov_b64_e32 v[152:153], s[14:15]
	v_mad_i64_i32 v[166:167], s[4:5], v156, s67, v[152:153]
	v_pk_mul_f32 v[128:129], v[128:129], v[164:165] op_sel_hi:[1,0]
	v_pk_mul_f32 v[126:127], v[126:127], v[164:165] op_sel_hi:[1,0]
	v_pk_mul_f32 v[168:169], v[124:125], v[164:165] op_sel_hi:[1,0]
	v_pk_mul_f32 v[124:125], v[122:123], v[164:165] op_sel_hi:[1,0]
	v_lshl_add_u64 v[166:167], v[166:167], 0, v[154:155]
	v_cvt_pk_bf16_f32 v122, v126, v127
	v_cvt_pk_bf16_f32 v123, v128, v129
	v_cvt_pk_bf16_f32 v124, v124, v125
	v_cvt_pk_bf16_f32 v125, v168, v169
	flat_store_dwordx4 v[166:167], v[122:125] nt
	v_pk_mul_f32 v[120:121], v[120:121], v[164:165] op_sel_hi:[1,0]
	v_pk_mul_f32 v[118:119], v[118:119], v[164:165] op_sel_hi:[1,0]
	v_pk_mul_f32 v[122:123], v[116:117], v[164:165] op_sel_hi:[1,0]
	v_pk_mul_f32 v[116:117], v[114:115], v[164:165] op_sel_hi:[1,0]
	v_or_b32_e32 v164, 16, v156
	v_cvt_pk_bf16_f32 v114, v118, v119
	v_cvt_pk_bf16_f32 v115, v120, v121
	v_cvt_pk_bf16_f32 v116, v116, v117
	v_cvt_pk_bf16_f32 v117, v122, v123
	v_ashrrev_i32_e32 v165, 31, v164
	flat_store_dwordx4 v[166:167], v[114:117] offset:256 nt
	s_nop 1
	v_lshlrev_b64 v[114:115], 6, v[164:165]
	v_lshl_add_u64 v[126:127], s[22:23], 0, v[114:115]
	flat_load_dwordx4 v[114:117], v[126:127]
	flat_load_dwordx4 v[118:121], v[126:127] offset:16
	flat_load_dwordx4 v[122:125], v[126:127] offset:32
	s_nop 0
	flat_load_dwordx4 v[126:129], v[126:127] offset:48
	s_waitcnt vmcnt(0) lgkmcnt(0)
	v_mov_b32_e32 v166, v114
	v_mov_b32_e32 v167, v122
	v_mov_b32_e32 v122, v115
	v_pk_add_f32 v[114:115], v[166:167], v[122:123]
	v_mov_b32_e32 v122, v116
	v_mov_b32_e32 v123, v124
	v_mov_b32_e32 v124, v117
	v_pk_add_f32 v[116:117], v[122:123], v[124:125]
	s_nop 0
	v_pk_add_f32 v[114:115], v[114:115], v[116:117]
	v_mov_b32_e32 v116, v118
	v_mov_b32_e32 v117, v126
	v_mov_b32_e32 v126, v119
	v_mov_b32_e32 v118, v120
	v_mov_b32_e32 v119, v128
	v_mov_b32_e32 v128, v121
	v_pk_add_f32 v[116:117], v[116:117], v[126:127]
	v_pk_add_f32 v[118:119], v[118:119], v[128:129]
	s_nop 0
	v_pk_add_f32 v[116:117], v[116:117], v[118:119]
	s_nop 0
	v_pk_add_f32 v[114:115], v[114:115], v[116:117]
	v_mad_i64_i32 v[116:117], s[4:5], v164, s67, v[152:153]
	v_add_f32_e32 v114, v114, v115
	v_fmamk_f32 v114, v114, 0x3a800000, v190
	v_cmp_gt_f32_e32 vcc, s66, v114
	v_mul_f32_e32 v115, 0x4b800000, v114
	v_lshl_add_u64 v[116:117], v[116:117], 0, v[154:155]
	v_cndmask_b32_e32 v114, v114, v115, vcc
	v_rsq_f32_e32 v114, v114
	s_nop 0
	v_mul_f32_e32 v115, 0x45800000, v114
	v_cndmask_b32_e32 v114, v114, v115, vcc
	v_pk_mul_f32 v[112:113], v[112:113], v[114:115] op_sel_hi:[1,0]
	v_pk_mul_f32 v[110:111], v[110:111], v[114:115] op_sel_hi:[1,0]
	v_pk_mul_f32 v[118:119], v[108:109], v[114:115] op_sel_hi:[1,0]
	v_pk_mul_f32 v[108:109], v[106:107], v[114:115] op_sel_hi:[1,0]
	v_cvt_pk_bf16_f32 v106, v110, v111
	v_cvt_pk_bf16_f32 v107, v112, v113
	v_cvt_pk_bf16_f32 v108, v108, v109
	v_cvt_pk_bf16_f32 v109, v118, v119
	flat_store_dwordx4 v[116:117], v[106:109] nt
	v_pk_mul_f32 v[104:105], v[104:105], v[114:115] op_sel_hi:[1,0]
	v_pk_mul_f32 v[102:103], v[102:103], v[114:115] op_sel_hi:[1,0]
	v_pk_mul_f32 v[106:107], v[100:101], v[114:115] op_sel_hi:[1,0]
	v_pk_mul_f32 v[100:101], v[98:99], v[114:115] op_sel_hi:[1,0]
	v_or_b32_e32 v114, 32, v156
	v_cvt_pk_bf16_f32 v98, v102, v103
	v_cvt_pk_bf16_f32 v99, v104, v105
	v_cvt_pk_bf16_f32 v100, v100, v101
	v_cvt_pk_bf16_f32 v101, v106, v107
	v_ashrrev_i32_e32 v115, 31, v114
	flat_store_dwordx4 v[116:117], v[98:101] offset:256 nt
	s_nop 1
	v_lshlrev_b64 v[98:99], 6, v[114:115]
	v_lshl_add_u64 v[110:111], s[22:23], 0, v[98:99]
	flat_load_dwordx4 v[98:101], v[110:111]
	flat_load_dwordx4 v[102:105], v[110:111] offset:16
	flat_load_dwordx4 v[106:109], v[110:111] offset:32
	s_nop 0
	flat_load_dwordx4 v[110:113], v[110:111] offset:48
	s_waitcnt vmcnt(0) lgkmcnt(0)
; __device__ __forceinline__ unsigned pk2(float lo, float hi) { f32x2 v = {lo, hi}; bf16x2_t b = __builtin_convertvector(v, bf16x2_t); return __builtin_bit_cast(unsigned, b); }
; __device__ __forceinline__ float ss_total(const float* ss, int row) { const f32x4* sp = (const f32x4*)(ss + (size_t)row * 16); const f32x4 a = sp[0], b = sp[1], c = sp[2], d = sp[3];
;     return (((a[0] + a[1]) + (a[2] + a[3])) + ((b[0] + b[1]) + (b[2] + b[3]))) + (((c[0] + c[1]) + (c[2] + c[3])) + ((d[0] + d[1]) + (d[2] + d[3]))); }
;     __device__ __forceinline__ void operator()(const f32x4 (&acc)[2][2][4][2], const pg8::Unit& u, int wr, int wc, int fr, int fq) const {
;         const int row0 = u.pm * 256 + wr * 64 + fr, col0 = u.pn * 256 + wc * 32 + 8 * fq;
; #pragma unroll
;         for (int ai = 0; ai < 2; ++ai)
; #pragma unroll
;             for (int m = 0; m < 4; ++m) { const int row = row0 + ai * 128 + m * 16; const float rs = rsqrtf(ss_total(ss, row) * (1.f / 1024.f) + EPS);
;                 bf16_t* rowp = O + (size_t)row * ldc + col0;
; #pragma unroll
;                 for (int bj = 0; bj < 2; ++bj) { const f32x4 v0 = acc[ai][bj][m][0] * rs, v1 = acc[ai][bj][m][1] * rs;
;                     u32x4 w; w.x = pk2(v0[0], v0[1]); w.y = pk2(v0[2], v0[3]); w.z = pk2(v1[0], v1[1]); w.w = pk2(v1[2], v1[3]);
;                     *(u32x4*)(rowp + bj * 128) = w; } }
	v_mov_b32_e32 v116, v98
	v_mov_b32_e32 v117, v106
	v_mov_b32_e32 v106, v99
	v_pk_add_f32 v[98:99], v[116:117], v[106:107]
	v_mov_b32_e32 v106, v100
	v_mov_b32_e32 v107, v108
	v_mov_b32_e32 v108, v101
	v_pk_add_f32 v[100:101], v[106:107], v[108:109]
	s_nop 0
	v_pk_add_f32 v[98:99], v[98:99], v[100:101]
	v_mov_b32_e32 v100, v102
	v_mov_b32_e32 v101, v110
	v_mov_b32_e32 v110, v103
	v_mov_b32_e32 v102, v104
	v_mov_b32_e32 v103, v112
	v_mov_b32_e32 v112, v105
	v_pk_add_f32 v[100:101], v[100:101], v[110:111]
	v_pk_add_f32 v[102:103], v[102:103], v[112:113]
	s_nop 0
	v_pk_add_f32 v[100:101], v[100:101], v[102:103]
	s_nop 0
	v_pk_add_f32 v[98:99], v[98:99], v[100:101]
	v_mad_i64_i32 v[100:101], s[4:5], v114, s67, v[152:153]
	v_add_f32_e32 v98, v98, v99
	v_fmamk_f32 v98, v98, 0x3a800000, v190
	v_cmp_gt_f32_e32 vcc, s66, v98
	v_mul_f32_e32 v99, 0x4b800000, v98
	v_lshl_add_u64 v[100:101], v[100:101], 0, v[154:155]
	v_cndmask_b32_e32 v98, v98, v99, vcc
	v_rsq_f32_e32 v98, v98
	s_nop 0
	v_mul_f32_e32 v99, 0x45800000, v98
	v_cndmask_b32_e32 v98, v98, v99, vcc
	v_pk_mul_f32 v[96:97], v[96:97], v[98:99] op_sel_hi:[1,0]
	v_pk_mul_f32 v[94:95], v[94:95], v[98:99] op_sel_hi:[1,0]
	v_pk_mul_f32 v[102:103], v[92:93], v[98:99] op_sel_hi:[1,0]
	v_pk_mul_f32 v[92:93], v[90:91], v[98:99] op_sel_hi:[1,0]
	v_cvt_pk_bf16_f32 v90, v94, v95
	v_cvt_pk_bf16_f32 v91, v96, v97
	v_cvt_pk_bf16_f32 v92, v92, v93
	v_cvt_pk_bf16_f32 v93, v102, v103
	flat_store_dwordx4 v[100:101], v[90:93] nt
	v_pk_mul_f32 v[88:89], v[88:89], v[98:99] op_sel_hi:[1,0]
	v_pk_mul_f32 v[86:87], v[86:87], v[98:99] op_sel_hi:[1,0]
	v_pk_mul_f32 v[90:91], v[84:85], v[98:99] op_sel_hi:[1,0]
	v_pk_mul_f32 v[84:85], v[82:83], v[98:99] op_sel_hi:[1,0]
	v_or_b32_e32 v98, 48, v156
	v_cvt_pk_bf16_f32 v82, v86, v87
	v_cvt_pk_bf16_f32 v83, v88, v89
	v_cvt_pk_bf16_f32 v84, v84, v85
	v_cvt_pk_bf16_f32 v85, v90, v91
	v_ashrrev_i32_e32 v99, 31, v98
	flat_store_dwordx4 v[100:101], v[82:85] offset:256 nt
	s_nop 1
	v_lshlrev_b64 v[82:83], 6, v[98:99]
	v_lshl_add_u64 v[94:95], s[22:23], 0, v[82:83]
	flat_load_dwordx4 v[82:85], v[94:95]
	flat_load_dwordx4 v[86:89], v[94:95] offset:16
	flat_load_dwordx4 v[90:93], v[94:95] offset:32
	s_nop 0
	flat_load_dwordx4 v[94:97], v[94:95] offset:48
	s_waitcnt vmcnt(0) lgkmcnt(0)
	v_mov_b32_e32 v100, v82
	v_mov_b32_e32 v101, v90
	v_mov_b32_e32 v90, v83
	v_pk_add_f32 v[82:83], v[100:101], v[90:91]
	v_mov_b32_e32 v90, v84
	v_mov_b32_e32 v91, v92
	v_mov_b32_e32 v92, v85
	v_pk_add_f32 v[84:85], v[90:91], v[92:93]
	s_nop 0
	v_pk_add_f32 v[82:83], v[82:83], v[84:85]
	v_mov_b32_e32 v84, v86
	v_mov_b32_e32 v85, v94
	v_mov_b32_e32 v94, v87
	v_mov_b32_e32 v86, v88
	v_mov_b32_e32 v87, v96
	v_mov_b32_e32 v96, v89
	v_pk_add_f32 v[84:85], v[84:85], v[94:95]
	v_pk_add_f32 v[86:87], v[86:87], v[96:97]
	s_nop 0
	v_pk_add_f32 v[84:85], v[84:85], v[86:87]
	s_nop 0
	v_pk_add_f32 v[82:83], v[82:83], v[84:85]
	v_mad_i64_i32 v[84:85], s[4:5], v98, s67, v[152:153]
	v_add_f32_e32 v82, v82, v83
	v_fmamk_f32 v82, v82, 0x3a800000, v190
	v_cmp_gt_f32_e32 vcc, s66, v82
	v_mul_f32_e32 v83, 0x4b800000, v82
	v_lshl_add_u64 v[84:85], v[84:85], 0, v[154:155]
	v_cndmask_b32_e32 v82, v82, v83, vcc
	v_rsq_f32_e32 v82, v82
	s_nop 0
	v_mul_f32_e32 v83, 0x45800000, v82
	v_cndmask_b32_e32 v82, v82, v83, vcc
	v_pk_mul_f32 v[80:81], v[80:81], v[82:83] op_sel_hi:[1,0]
	v_pk_mul_f32 v[78:79], v[78:79], v[82:83] op_sel_hi:[1,0]
	v_pk_mul_f32 v[86:87], v[76:77], v[82:83] op_sel_hi:[1,0]
	v_pk_mul_f32 v[76:77], v[74:75], v[82:83] op_sel_hi:[1,0]
	v_cvt_pk_bf16_f32 v74, v78, v79
	v_cvt_pk_bf16_f32 v75, v80, v81
	v_cvt_pk_bf16_f32 v76, v76, v77
	v_cvt_pk_bf16_f32 v77, v86, v87
	flat_store_dwordx4 v[84:85], v[74:77] nt
	v_pk_mul_f32 v[72:73], v[72:73], v[82:83] op_sel_hi:[1,0]
	v_pk_mul_f32 v[70:71], v[70:71], v[82:83] op_sel_hi:[1,0]
	v_pk_mul_f32 v[74:75], v[68:69], v[82:83] op_sel_hi:[1,0]
	v_pk_mul_f32 v[68:69], v[66:67], v[82:83] op_sel_hi:[1,0]
	v_add_u32_e32 v82, 0x80, v156
	v_cvt_pk_bf16_f32 v66, v70, v71
	v_cvt_pk_bf16_f32 v67, v72, v73
	v_cvt_pk_bf16_f32 v68, v68, v69
	v_cvt_pk_bf16_f32 v69, v74, v75
	v_ashrrev_i32_e32 v83, 31, v82
	flat_store_dwordx4 v[84:85], v[66:69] offset:256 nt
	s_nop 1
	v_lshlrev_b64 v[66:67], 6, v[82:83]
	v_lshl_add_u64 v[78:79], s[22:23], 0, v[66:67]
	flat_load_dwordx4 v[66:69], v[78:79]
	flat_load_dwordx4 v[70:73], v[78:79] offset:16
	flat_load_dwordx4 v[74:77], v[78:79] offset:32
	s_nop 0
	flat_load_dwordx4 v[78:81], v[78:79] offset:48
	s_waitcnt vmcnt(0) lgkmcnt(0)
	v_mov_b32_e32 v84, v66
	v_mov_b32_e32 v85, v74
	v_mov_b32_e32 v74, v67
	v_pk_add_f32 v[66:67], v[84:85], v[74:75]
	v_mov_b32_e32 v74, v68
	v_mov_b32_e32 v75, v76
	v_mov_b32_e32 v76, v69
	v_pk_add_f32 v[68:69], v[74:75], v[76:77]
	s_nop 0
	v_pk_add_f32 v[66:67], v[66:67], v[68:69]
	v_mov_b32_e32 v68, v70
	v_mov_b32_e32 v69, v78
	v_mov_b32_e32 v78, v71
	v_mov_b32_e32 v70, v72
	v_mov_b32_e32 v71, v80
	v_mov_b32_e32 v80, v73
	v_pk_add_f32 v[68:69], v[68:69], v[78:79]
	v_pk_add_f32 v[70:71], v[70:71], v[80:81]
	s_nop 0
	v_pk_add_f32 v[68:69], v[68:69], v[70:71]
	s_nop 0
	v_pk_add_f32 v[66:67], v[66:67], v[68:69]
	v_mad_i64_i32 v[68:69], s[4:5], v82, s67, v[152:153]
	v_add_f32_e32 v66, v66, v67
	v_fmamk_f32 v66, v66, 0x3a800000, v190
	v_cmp_gt_f32_e32 vcc, s66, v66
	v_mul_f32_e32 v67, 0x4b800000, v66
	v_lshl_add_u64 v[68:69], v[68:69], 0, v[154:155]
	v_cndmask_b32_e32 v66, v66, v67, vcc
	v_rsq_f32_e32 v66, v66
	s_nop 0
	v_mul_f32_e32 v67, 0x45800000, v66
	v_cndmask_b32_e32 v66, v66, v67, vcc
	v_pk_mul_f32 v[64:65], v[64:65], v[66:67] op_sel_hi:[1,0]
	v_pk_mul_f32 v[62:63], v[62:63], v[66:67] op_sel_hi:[1,0]
	v_pk_mul_f32 v[70:71], v[60:61], v[66:67] op_sel_hi:[1,0]
	v_pk_mul_f32 v[60:61], v[58:59], v[66:67] op_sel_hi:[1,0]
	v_cvt_pk_bf16_f32 v58, v62, v63
	v_cvt_pk_bf16_f32 v59, v64, v65
	v_cvt_pk_bf16_f32 v60, v60, v61
	v_cvt_pk_bf16_f32 v61, v70, v71
	flat_store_dwordx4 v[68:69], v[58:61] nt
	v_pk_mul_f32 v[56:57], v[56:57], v[66:67] op_sel_hi:[1,0]
	v_pk_mul_f32 v[54:55], v[54:55], v[66:67] op_sel_hi:[1,0]
	v_pk_mul_f32 v[58:59], v[52:53], v[66:67] op_sel_hi:[1,0]
	v_pk_mul_f32 v[52:53], v[50:51], v[66:67] op_sel_hi:[1,0]
	v_add_u32_e32 v66, 0x90, v156
	v_cvt_pk_bf16_f32 v50, v54, v55
	v_cvt_pk_bf16_f32 v51, v56, v57
	v_cvt_pk_bf16_f32 v52, v52, v53
	v_cvt_pk_bf16_f32 v53, v58, v59
	v_ashrrev_i32_e32 v67, 31, v66
	flat_store_dwordx4 v[68:69], v[50:53] offset:256 nt
	s_nop 1
	v_lshlrev_b64 v[50:51], 6, v[66:67]
	v_lshl_add_u64 v[62:63], s[22:23], 0, v[50:51]
	flat_load_dwordx4 v[50:53], v[62:63]
	flat_load_dwordx4 v[54:57], v[62:63] offset:16
	flat_load_dwordx4 v[58:61], v[62:63] offset:32
	s_nop 0
	flat_load_dwordx4 v[62:65], v[62:63] offset:48
	s_waitcnt vmcnt(0) lgkmcnt(0)
; __device__ __forceinline__ unsigned pk2(float lo, float hi) { f32x2 v = {lo, hi}; bf16x2_t b = __builtin_convertvector(v, bf16x2_t); return __builtin_bit_cast(unsigned, b); }
; __device__ __forceinline__ float ss_total(const float* ss, int row) { const f32x4* sp = (const f32x4*)(ss + (size_t)row * 16); const f32x4 a = sp[0], b = sp[1], c = sp[2], d = sp[3];
;     return (((a[0] + a[1]) + (a[2] + a[3])) + ((b[0] + b[1]) + (b[2] + b[3]))) + (((c[0] + c[1]) + (c[2] + c[3])) + ((d[0] + d[1]) + (d[2] + d[3]))); }
;     __device__ __forceinline__ void operator()(const f32x4 (&acc)[2][2][4][2], const pg8::Unit& u, int wr, int wc, int fr, int fq) const {
;     ...
;             for (int m = 0; m < 4; ++m) { const int row = row0 + ai * 128 + m * 16; const float rs = rsqrtf(ss_total(ss, row) * (1.f / 1024.f) + EPS);
;                 bf16_t* rowp = O + (size_t)row * ldc + col0;
; #pragma unroll
;                 for (int bj = 0; bj < 2; ++bj) { const f32x4 v0 = acc[ai][bj][m][0] * rs, v1 = acc[ai][bj][m][1] * rs;
;                     u32x4 w; w.x = pk2(v0[0], v0[1]); w.y = pk2(v0[2], v0[3]); w.z = pk2(v1[0], v1[1]); w.w = pk2(v1[2], v1[3]);
;                     *(u32x4*)(rowp + bj * 128) = w; } }
	v_mov_b32_e32 v68, v50
	v_mov_b32_e32 v69, v58
	v_mov_b32_e32 v58, v51
	v_pk_add_f32 v[50:51], v[68:69], v[58:59]
	v_mov_b32_e32 v58, v52
	v_mov_b32_e32 v59, v60
	v_mov_b32_e32 v60, v53
	v_pk_add_f32 v[52:53], v[58:59], v[60:61]
	s_nop 0
	v_pk_add_f32 v[50:51], v[50:51], v[52:53]
	v_mov_b32_e32 v52, v54
	v_mov_b32_e32 v53, v62
	v_mov_b32_e32 v62, v55
	v_mov_b32_e32 v54, v56
	v_mov_b32_e32 v55, v64
	v_mov_b32_e32 v64, v57
	v_pk_add_f32 v[52:53], v[52:53], v[62:63]
	v_pk_add_f32 v[54:55], v[54:55], v[64:65]
	s_nop 0
	v_pk_add_f32 v[52:53], v[52:53], v[54:55]
	s_nop 0
	v_pk_add_f32 v[50:51], v[50:51], v[52:53]
	v_mad_i64_i32 v[52:53], s[4:5], v66, s67, v[152:153]
	v_add_f32_e32 v50, v50, v51
	v_fmamk_f32 v50, v50, 0x3a800000, v190
	v_cmp_gt_f32_e32 vcc, s66, v50
	v_mul_f32_e32 v51, 0x4b800000, v50
	v_lshl_add_u64 v[52:53], v[52:53], 0, v[154:155]
	v_cndmask_b32_e32 v50, v50, v51, vcc
	v_rsq_f32_e32 v50, v50
	s_nop 0
	v_mul_f32_e32 v51, 0x45800000, v50
	v_cndmask_b32_e32 v50, v50, v51, vcc
	v_pk_mul_f32 v[48:49], v[48:49], v[50:51] op_sel_hi:[1,0]
	v_pk_mul_f32 v[46:47], v[46:47], v[50:51] op_sel_hi:[1,0]
	v_pk_mul_f32 v[54:55], v[44:45], v[50:51] op_sel_hi:[1,0]
	v_pk_mul_f32 v[44:45], v[42:43], v[50:51] op_sel_hi:[1,0]
	v_cvt_pk_bf16_f32 v42, v46, v47
	v_cvt_pk_bf16_f32 v43, v48, v49
	v_cvt_pk_bf16_f32 v44, v44, v45
	v_cvt_pk_bf16_f32 v45, v54, v55
	flat_store_dwordx4 v[52:53], v[42:45] nt
	v_pk_mul_f32 v[40:41], v[40:41], v[50:51] op_sel_hi:[1,0]
	v_pk_mul_f32 v[38:39], v[38:39], v[50:51] op_sel_hi:[1,0]
	v_pk_mul_f32 v[42:43], v[36:37], v[50:51] op_sel_hi:[1,0]
	v_pk_mul_f32 v[36:37], v[34:35], v[50:51] op_sel_hi:[1,0]
	v_add_u32_e32 v50, 0xa0, v156
	v_cvt_pk_bf16_f32 v34, v38, v39
	v_cvt_pk_bf16_f32 v35, v40, v41
	v_cvt_pk_bf16_f32 v36, v36, v37
	v_cvt_pk_bf16_f32 v37, v42, v43
	v_ashrrev_i32_e32 v51, 31, v50
	flat_store_dwordx4 v[52:53], v[34:37] offset:256 nt
	s_nop 1
	v_lshlrev_b64 v[34:35], 6, v[50:51]
	v_lshl_add_u64 v[46:47], s[22:23], 0, v[34:35]
	flat_load_dwordx4 v[34:37], v[46:47]
	flat_load_dwordx4 v[38:41], v[46:47] offset:16
	flat_load_dwordx4 v[42:45], v[46:47] offset:32
	s_nop 0
	flat_load_dwordx4 v[46:49], v[46:47] offset:48
	s_waitcnt vmcnt(0) lgkmcnt(0)
	v_mov_b32_e32 v52, v34
	v_mov_b32_e32 v53, v42
	v_mov_b32_e32 v42, v35
	v_pk_add_f32 v[34:35], v[52:53], v[42:43]
	v_mov_b32_e32 v42, v36
	v_mov_b32_e32 v43, v44
	v_mov_b32_e32 v44, v37
	v_pk_add_f32 v[36:37], v[42:43], v[44:45]
	s_nop 0
	v_pk_add_f32 v[34:35], v[34:35], v[36:37]
	v_mov_b32_e32 v36, v38
	v_mov_b32_e32 v37, v46
	v_mov_b32_e32 v46, v39
	v_mov_b32_e32 v38, v40
	v_mov_b32_e32 v39, v48
	v_mov_b32_e32 v48, v41
	v_pk_add_f32 v[36:37], v[36:37], v[46:47]
	v_pk_add_f32 v[38:39], v[38:39], v[48:49]
	s_nop 0
	v_pk_add_f32 v[36:37], v[36:37], v[38:39]
	s_nop 0
	v_pk_add_f32 v[34:35], v[34:35], v[36:37]
	v_mad_i64_i32 v[36:37], s[4:5], v50, s67, v[152:153]
	v_add_f32_e32 v34, v34, v35
	v_fmamk_f32 v34, v34, 0x3a800000, v190
	v_cmp_gt_f32_e32 vcc, s66, v34
	v_mul_f32_e32 v35, 0x4b800000, v34
	v_lshl_add_u64 v[36:37], v[36:37], 0, v[154:155]
	v_cndmask_b32_e32 v34, v34, v35, vcc
	v_rsq_f32_e32 v34, v34
	s_nop 0
	v_mul_f32_e32 v35, 0x45800000, v34
	v_cndmask_b32_e32 v34, v34, v35, vcc
	v_pk_mul_f32 v[32:33], v[32:33], v[34:35] op_sel_hi:[1,0]
	v_pk_mul_f32 v[30:31], v[30:31], v[34:35] op_sel_hi:[1,0]
	v_pk_mul_f32 v[38:39], v[28:29], v[34:35] op_sel_hi:[1,0]
	v_pk_mul_f32 v[28:29], v[26:27], v[34:35] op_sel_hi:[1,0]
	v_cvt_pk_bf16_f32 v26, v30, v31
	v_cvt_pk_bf16_f32 v27, v32, v33
	v_cvt_pk_bf16_f32 v28, v28, v29
	v_cvt_pk_bf16_f32 v29, v38, v39
	flat_store_dwordx4 v[36:37], v[26:29] nt
	v_pk_mul_f32 v[24:25], v[24:25], v[34:35] op_sel_hi:[1,0]
	v_pk_mul_f32 v[22:23], v[22:23], v[34:35] op_sel_hi:[1,0]
	v_pk_mul_f32 v[26:27], v[20:21], v[34:35] op_sel_hi:[1,0]
	v_pk_mul_f32 v[20:21], v[18:19], v[34:35] op_sel_hi:[1,0]
	v_add_u32_e32 v34, 0xb0, v156
	v_cvt_pk_bf16_f32 v18, v22, v23
	v_cvt_pk_bf16_f32 v19, v24, v25
	v_cvt_pk_bf16_f32 v20, v20, v21
	v_cvt_pk_bf16_f32 v21, v26, v27
	v_ashrrev_i32_e32 v35, 31, v34
	flat_store_dwordx4 v[36:37], v[18:21] offset:256 nt
	s_nop 1
	v_lshlrev_b64 v[18:19], 6, v[34:35]
	v_lshl_add_u64 v[30:31], s[22:23], 0, v[18:19]
	flat_load_dwordx4 v[18:21], v[30:31]
	flat_load_dwordx4 v[22:25], v[30:31] offset:16
	flat_load_dwordx4 v[26:29], v[30:31] offset:32
	s_nop 0
	flat_load_dwordx4 v[30:33], v[30:31] offset:48
	s_waitcnt vmcnt(0) lgkmcnt(0)
	v_mov_b32_e32 v36, v18
	v_mov_b32_e32 v37, v26
	v_mov_b32_e32 v26, v19
	v_pk_add_f32 v[18:19], v[36:37], v[26:27]
	v_mov_b32_e32 v26, v20
	v_mov_b32_e32 v27, v28
	v_mov_b32_e32 v28, v21
	v_pk_add_f32 v[20:21], v[26:27], v[28:29]
	s_nop 0
	v_pk_add_f32 v[18:19], v[18:19], v[20:21]
	v_mov_b32_e32 v20, v22
	v_mov_b32_e32 v21, v30
	v_mov_b32_e32 v30, v23
	v_mov_b32_e32 v22, v24
	v_mov_b32_e32 v23, v32
	v_mov_b32_e32 v32, v25
	v_pk_add_f32 v[20:21], v[20:21], v[30:31]
	v_pk_add_f32 v[22:23], v[22:23], v[32:33]
	s_nop 0
	v_pk_add_f32 v[20:21], v[20:21], v[22:23]
	s_nop 0
	v_pk_add_f32 v[18:19], v[18:19], v[20:21]
	v_mad_i64_i32 v[20:21], s[4:5], v34, s67, v[152:153]
	v_add_f32_e32 v18, v18, v19
	v_fmamk_f32 v18, v18, 0x3a800000, v190
	v_cmp_gt_f32_e32 vcc, s66, v18
	v_mul_f32_e32 v19, 0x4b800000, v18
	v_lshl_add_u64 v[20:21], v[20:21], 0, v[154:155]
	v_cndmask_b32_e32 v18, v18, v19, vcc
	v_rsq_f32_e32 v18, v18
	s_mov_b64 s[4:5], -1
	v_mul_f32_e32 v19, 0x45800000, v18
	v_cndmask_b32_e32 v18, v18, v19, vcc
	v_pk_mul_f32 v[16:17], v[16:17], v[18:19] op_sel_hi:[1,0]
	v_pk_mul_f32 v[14:15], v[14:15], v[18:19] op_sel_hi:[1,0]
	v_pk_mul_f32 v[22:23], v[12:13], v[18:19] op_sel_hi:[1,0]
	v_pk_mul_f32 v[12:13], v[10:11], v[18:19] op_sel_hi:[1,0]
	v_cvt_pk_bf16_f32 v10, v14, v15
	v_cvt_pk_bf16_f32 v11, v16, v17
	v_cvt_pk_bf16_f32 v12, v12, v13
	v_cvt_pk_bf16_f32 v13, v22, v23
	flat_store_dwordx4 v[20:21], v[10:13] nt
	v_pk_mul_f32 v[8:9], v[8:9], v[18:19] op_sel_hi:[1,0]
	v_pk_mul_f32 v[6:7], v[6:7], v[18:19] op_sel_hi:[1,0]
	v_pk_mul_f32 v[10:11], v[4:5], v[18:19] op_sel_hi:[1,0]
	v_pk_mul_f32 v[4:5], v[2:3], v[18:19] op_sel_hi:[1,0]
	v_cvt_pk_bf16_f32 v2, v6, v7
	v_cvt_pk_bf16_f32 v3, v8, v9
	v_cvt_pk_bf16_f32 v4, v4, v5
	v_cvt_pk_bf16_f32 v5, v10, v11
	s_andn2_b64 vcc, exec, s[38:39]
	flat_store_dwordx4 v[20:21], v[2:5] offset:256 nt
	s_branch .Lp1_epi_join
.Lp1_epi_after:
	s_andn2_b64 vcc, exec, s[0:1]
	s_cbranch_vccnz .LBB0_125
	s_barrier
	s_branch .LBB0_125
